# dil attention: V-tile LDS write waits count only the V loads (vmcnt 15..8) while the next K prefetch is in flight, instead of draining it (on top of v7)
# baseline (speedup 1.0000x reference)
; #define LAS __attribute__((address_space(3)))
; __device__ __forceinline__ bool dil_inrange(int pos0, int d, int u0) { return (pos0 + d * u0 >= 0) && (pos0 + d * (u0 + 31) < SEQ); }
; __device__ __forceinline__ void v_to_lds(LAS unsigned char* vt, const bf16x8 (&vn)[8], int lane) {
; #pragma unroll
;     for (int it = 0; it < 8; ++it) *(LAS bf16x8*)(vt + off_b(it * 4 + (lane >> 4), lane & 15)) = vn[it];
; }
; __device__ __forceinline__ void dil_loadv(bf16x8 (&vn)[8], const bf16* Vb, int pos0, int d, int u0, int fq) {
;     if (dil_inrange(pos0, d, u0)) {
;         const bf16* p = Vb + (size_t)(pos0 + d * (u0 + fq)) * 128; const size_t step = (size_t)(512 * d);
; #pragma unroll
;         for (int it = 0; it < 8; ++it) vn[it] = *(const bf16x8*)(p + (size_t)it * step);
;     } else {
; #pragma unroll
;         for (int it = 0; it < 8; ++it) { int pos = pos0 + d * (u0 + it * 4 + fq); pos = pos < 0 ? 0 : (pos > SEQ - 1 ? SEQ - 1 : pos); vn[it] = *(const bf16x8*)(Vb + (size_t)pos * 128); }
;     }
.LBB0_1564:
	s_add_i32 s8, s27, 1
	s_cmp_lt_u32 s8, s24
	s_cselect_b64 s[6:7], -1, 0
	s_cmp_ge_u32 s8, s24
	s_cbranch_scc1 .Ldil_lad7a
	s_waitcnt vmcnt(15)
	ds_write_b128 v203, v[72:75]
	s_waitcnt vmcnt(14)
	ds_write_b128 v204, v[68:71]
	s_waitcnt vmcnt(13)
	ds_write_b128 v205, v[80:83]
	s_waitcnt vmcnt(12)
	ds_write_b128 v206, v[76:79]
	s_waitcnt vmcnt(11)
	ds_write_b128 v207, v[88:91]
	s_waitcnt vmcnt(10)
	ds_write_b128 v208, v[84:87]
	s_waitcnt vmcnt(9)
	ds_write_b128 v209, v[92:95]
	s_waitcnt vmcnt(8)
	ds_write_b128 v210, v[128:131]
	s_branch .Ldil_ladja
.Ldil_lad7a:
	s_waitcnt vmcnt(7)
	ds_write_b128 v203, v[72:75]
	s_waitcnt vmcnt(6)
	ds_write_b128 v204, v[68:71]
	s_waitcnt vmcnt(5)
	ds_write_b128 v205, v[80:83]
	s_waitcnt vmcnt(4)
	ds_write_b128 v206, v[76:79]
	s_waitcnt vmcnt(3)
	ds_write_b128 v207, v[88:91]
	s_waitcnt vmcnt(2)
	ds_write_b128 v208, v[84:87]
	s_waitcnt vmcnt(1)
	ds_write_b128 v209, v[92:95]
	s_waitcnt vmcnt(0)
	ds_write_b128 v210, v[128:131]
.Ldil_ladja:
	s_cbranch_scc1 .LBB0_1570
	s_add_i32 s8, s5, 0xffffffa1
	s_lshl_b32 s8, s8, s23
	s_cmp_gt_i32 s8, s74
	s_cselect_b64 s[8:9], -1, 0
	s_sub_i32 s10, s5, 64
	s_lshl_b32 s10, s10, s23
	s_cmp_lt_i32 s10, s22
	v_add_u32_e32 v129, s5, v166
	s_cselect_b64 s[10:11], -1, 0
	v_add_u32_e32 v0, 0xffffffa1, v129
	s_and_b64 s[10:11], s[8:9], s[10:11]
	v_lshlrev_b32_e32 v0, s23, v0
	v_add_u32_e32 v128, s65, v0
	s_mov_b64 s[8:9], -1
	s_and_b64 vcc, exec, s[10:11]
	s_cbranch_vccnz .LBB0_1567
	v_med3_i32 v0, v128, 0, v225
	v_lshlrev_b32_e32 v0, 8, v0
	v_lshl_add_u64 v[68:69], v[160:161], 0, v[0:1]
	v_add_u32_e32 v0, 0xffffffa5, v129
	v_lshlrev_b32_e32 v0, s23, v0
	v_add_u32_e32 v0, s65, v0
	v_med3_i32 v0, v0, 0, v225
	v_lshlrev_b32_e32 v0, 8, v0
	v_lshl_add_u64 v[70:71], v[160:161], 0, v[0:1]
	v_add_u32_e32 v0, 0xffffffa9, v129
	v_lshlrev_b32_e32 v0, s23, v0
	v_add_u32_e32 v0, s65, v0
	v_med3_i32 v0, v0, 0, v225
	v_lshlrev_b32_e32 v0, 8, v0
	v_lshl_add_u64 v[76:77], v[160:161], 0, v[0:1]
	v_add_u32_e32 v0, 0xffffffad, v129
	v_lshlrev_b32_e32 v0, s23, v0
	v_add_u32_e32 v0, s65, v0
	v_med3_i32 v0, v0, 0, v225
	v_lshlrev_b32_e32 v0, 8, v0
	v_lshl_add_u64 v[78:79], v[160:161], 0, v[0:1]
	v_add_u32_e32 v0, 0xffffffb1, v129
	v_lshlrev_b32_e32 v0, s23, v0
	v_add_u32_e32 v0, s65, v0
	v_med3_i32 v0, v0, 0, v225
	v_lshlrev_b32_e32 v0, 8, v0
	v_lshl_add_u64 v[84:85], v[160:161], 0, v[0:1]
	v_add_u32_e32 v0, 0xffffffb5, v129
	v_lshlrev_b32_e32 v0, s23, v0
	v_add_u32_e32 v0, s65, v0
	v_med3_i32 v0, v0, 0, v225
	v_lshlrev_b32_e32 v0, 8, v0
	v_lshl_add_u64 v[86:87], v[160:161], 0, v[0:1]
	v_add_u32_e32 v0, 0xffffffb9, v129
	v_lshlrev_b32_e32 v0, s23, v0
	v_add_u32_e32 v0, s65, v0
	v_med3_i32 v0, v0, 0, v225
	v_lshlrev_b32_e32 v0, 8, v0
	v_lshl_add_u64 v[92:93], v[160:161], 0, v[0:1]
	global_load_dwordx4 v[72:75], v[68:69], off
	s_nop 0
	global_load_dwordx4 v[68:71], v[70:71], off
	s_nop 0
	global_load_dwordx4 v[80:83], v[76:77], off
	s_nop 0
	global_load_dwordx4 v[76:79], v[78:79], off
	s_nop 0
	global_load_dwordx4 v[88:91], v[84:85], off
	s_nop 0
	global_load_dwordx4 v[84:87], v[86:87], off
	v_add_u32_e32 v0, 0xffffffbd, v129
	global_load_dwordx4 v[92:95], v[92:93], off
	v_lshlrev_b32_e32 v0, s23, v0
	v_add_u32_e32 v0, s65, v0
	v_med3_i32 v0, v0, 0, v225
	v_lshlrev_b32_e32 v0, 8, v0
	v_lshl_add_u64 v[130:131], v[160:161], 0, v[0:1]
	s_mov_b64 s[8:9], 0

; __device__ __forceinline__ unsigned cvt_pk_bf16(float lo, float hi) { unsigned r; asm volatile("v_cvt_pk_bf16_f32 %0, %1, %2" : "=v"(r) : "v"(lo), "v"(hi)); return r; }
; __device__ __forceinline__ s16x4 vtr(const LAS unsigned char* p) { return __builtin_bit_cast(s16x4, __builtin_amdgcn_ds_read_tr16_b64_v4i16((LAS s16x4*)p)); }
; __device__ __forceinline__ bf16x8 cat4(s16x4 a, s16x4 b) { return __builtin_shufflevector(a, b, 0, 1, 2, 3, 4, 5, 6, 7); }
; template <class Bias>
; __device__ __forceinline__ void attn_softmax_pv(const f32x4& sa, const f32x4& sb, float ra, float rb, const LAS unsigned char* vt, int lane, float& m, float& l, f32x4 (&O)[8], Bias bias) {
;     ...
;     for (int e = 0; e < 4; ++e) {
;         const float rka = __shfl(ra, 20 * fq + e), rkb = __shfl(rb, 20 * fq + e);
;         sv[e] = bias(e, sa[e] * rka); sv[4 + e] = bias(4 + e, sb[e] * rkb);
;     }
;     float mx = fmaxf(fmaxf(fmaxf(sv[0], sv[1]), fmaxf(sv[2], sv[3])), fmaxf(fmaxf(sv[4], sv[5]), fmaxf(sv[6], sv[7])));
;     mx = fmaxf(mx, __shfl_xor(mx, 16)); mx = fmaxf(mx, __shfl_xor(mx, 32));
;     const bool resc = __builtin_amdgcn_ballot_w64(mx - m > 5.5f) != 0ull;
;     float corr = 1.0f;
;     if (resc) { const float mn = fmaxf(m, mx); corr = __expf(m - mn); m = mn; }
;     float p[8], ps = 0.f;
; #pragma unroll
;     for (int e = 0; e < 8; ++e) { p[e] = __expf(sv[e] - m); ps += p[e]; }
;     l = l * corr + ps;
;     u32x4 pw; pw.x = cvt_pk_bf16(p[0], p[1]); pw.y = cvt_pk_bf16(p[2], p[3]); pw.z = cvt_pk_bf16(p[4], p[5]); pw.w = cvt_pk_bf16(p[6], p[7]);
;     const bf16x8 pf = __builtin_bit_cast(bf16x8, pw);
; #pragma unroll
;     for (int db = 0; db < 8; ++db) {
;         const s16x4 v0 = vtr(vt + tra.b0 + 32u * ((unsigned)db ^ tra.x0)), v1 = vtr(vt + tra.b1 + 32u * ((unsigned)db ^ tra.x1));
;         if (resc) O[db] = O[db] * corr;
;         O[db] = __builtin_amdgcn_mfma_f32_16x16x32_bf16(cat4(v0, v1), pf, O[db], 0, 0, 0);
;     }
.LBB0_1592:
	s_or_b64 exec, exec, s[60:61]
	v_add_u32_e32 v137, 0xffffff87, v0
	v_add_u32_e32 v138, 0xffffff87, v147
	v_sub_u32_e32 v139, 0x79, v147
	v_lshlrev_b32_e32 v137, s23, v137
	v_max_i32_e32 v138, v138, v139
	v_add_u32_e32 v137, s65, v137
	v_cmp_gt_u32_e64 s[60:61], s3, v137
	v_cvt_f32_u32_e32 v137, v138
	v_cmp_gt_u32_e32 vcc, s45, v138
	v_add_u32_e32 v138, 0xffffff86, v147
	v_sub_u32_e32 v139, 0x7a, v147
	v_mul_f32_e32 v137, v163, v137
	s_waitcnt lgkmcnt(2)
	v_fma_f32 v134, v134, v228, -v137
	v_add_u32_e32 v137, 0xffffff86, v0
	v_lshlrev_b32_e32 v137, s23, v137
	v_max_i32_e32 v138, v138, v139
	v_add_u32_e32 v137, s65, v137
	s_or_b64 s[28:29], s[10:11], s[60:61]
	v_cmp_gt_u32_e64 s[60:61], s3, v137
	v_cvt_f32_u32_e32 v137, v138
	s_and_b64 vcc, vcc, s[28:29]
	v_cndmask_b32_e32 v134, v227, v134, vcc
	v_cmp_gt_u32_e32 vcc, s45, v138
	s_or_b64 s[28:29], s[10:11], s[60:61]
	v_mul_f32_e32 v137, v163, v137
	v_fma_f32 v133, v133, v214, -v137
	s_and_b64 vcc, vcc, s[28:29]
	v_cndmask_b32_e32 v138, v227, v133, vcc
	v_add_u32_e32 v133, 0xffffff85, v0
	v_add_u32_e32 v137, 0xffffff85, v147
	v_sub_u32_e32 v139, 0x7b, v147
	v_lshlrev_b32_e32 v133, s23, v133
	v_max_i32_e32 v137, v137, v139
	v_add_u32_e32 v133, s65, v133
	v_cmp_gt_u32_e64 s[60:61], s3, v133
	v_cvt_f32_u32_e32 v133, v137
	v_cmp_gt_u32_e32 vcc, s45, v137
	s_or_b64 s[28:29], s[10:11], s[60:61]
	s_and_b64 vcc, vcc, s[28:29]
	v_mul_f32_e32 v133, v163, v133
	v_fma_f32 v132, v132, v212, -v133
	v_cndmask_b32_e32 v139, v227, v132, vcc
	v_add_u32_e32 v132, 0xffffff88, v147
	v_sub_u32_e32 v133, 0x78, v147
	v_max_i32_e32 v132, v132, v133
	v_add_u32_e32 v0, 0xffffff88, v0
	v_cvt_f32_u32_e32 v137, v132
	v_lshlrev_b32_e32 v0, s23, v0
	v_add_u32_e32 v0, s65, v0
	v_cmp_gt_u32_e64 s[60:61], s3, v0
	v_mov_b32_e32 v162, v135
	v_cmp_gt_u32_e32 vcc, s45, v132
	s_or_b64 s[10:11], s[10:11], s[60:61]
	s_waitcnt lgkmcnt(0)
	v_pk_mul_f32 v[132:133], v[162:163], v[136:137]
	s_and_b64 vcc, vcc, s[10:11]
	v_sub_f32_e32 v0, v132, v133
	v_cndmask_b32_e32 v132, v227, v0, vcc
	v_max_f32_e32 v0, v144, v144
	v_max_f32_e32 v133, v145, v145
	v_max_f32_e32 v0, v133, v0
	v_max_f32_e32 v133, v141, v141
	v_max_f32_e32 v135, v146, v146
	v_max_f32_e32 v133, v135, v133
	v_max_f32_e32 v135, v134, v132
	v_max3_f32 v135, v139, v138, v135
	v_max3_f32 v0, v0, v133, v135
	ds_bpermute_b32 v133, v167, v0
	v_bfe_u32 v136, v143, 2, 2
	v_lshlrev_b32_e32 v137, 3, v143
	v_lshlrev_b32_e32 v135, 11, v142
	v_and_b32_e32 v137, 24, v137
	s_waitcnt lgkmcnt(0)
	v_max_f32_e32 v133, v133, v133
	v_max_f32_e32 v0, v0, v133
	ds_bpermute_b32 v133, v168, v0
	v_lshlrev_b32_e32 v147, 5, v142
	v_and_b32_e32 v162, 32, v147
	s_waitcnt lgkmcnt(0)
	v_max_f32_e32 v133, v133, v133
	v_max_f32_e32 v0, v0, v133
	v_sub_f32_e32 v133, v0, v201
	v_cmp_lt_f32_e32 vcc, s92, v133
	v_max_f32_e32 v133, v201, v201
	v_max_f32_e32 v0, v133, v0
	v_sub_f32_e32 v133, v201, v0
	v_mul_f32_e32 v133, 0x3fb8aa3b, v133
	v_exp_f32_e32 v133, v133
	s_cmp_eq_u64 vcc, 0
	s_cselect_b64 vcc, -1, 0
	v_cndmask_b32_e32 v201, v0, v201, vcc
	v_cndmask_b32_e64 v0, v133, 1.0, vcc
	v_lshlrev_b32_e32 v133, 8, v136
	v_or3_b32 v137, v133, v135, v137
	v_sub_f32_e32 v133, v145, v201
	v_mul_f32_e32 v133, 0x3fb8aa3b, v133
	v_sub_f32_e32 v140, v144, v201
	v_exp_f32_e32 v133, v133
	v_mul_f32_e32 v140, 0x3fb8aa3b, v140
	v_sub_f32_e32 v143, v146, v201
	v_exp_f32_e32 v140, v140
	v_mul_f32_e32 v143, 0x3fb8aa3b, v143
	v_sub_f32_e32 v141, v141, v201
	v_exp_f32_e32 v143, v143
	v_mul_f32_e32 v141, 0x3fb8aa3b, v141
	v_sub_f32_e32 v139, v139, v201
	v_exp_f32_e32 v141, v141
	v_mul_f32_e32 v139, 0x3fb8aa3b, v139
	v_sub_f32_e32 v138, v138, v201
	v_add_f32_e32 v135, 0, v133
	v_exp_f32_e32 v139, v139
	v_mul_f32_e32 v138, 0x3fb8aa3b, v138
	v_sub_f32_e32 v134, v134, v201
	v_add_f32_e32 v135, v140, v135
	v_exp_f32_e32 v138, v138
	v_mul_f32_e32 v134, 0x3fb8aa3b, v134
	v_add_f32_e32 v135, v143, v135
	v_exp_f32_e32 v144, v134
	v_add_f32_e32 v135, v141, v135
	v_add_f32_e32 v135, v139, v135
	v_sub_f32_e32 v132, v132, v201
	v_add_f32_e32 v135, v138, v135
	v_mul_f32_e32 v132, 0x3fb8aa3b, v132
	v_add_f32_e32 v134, v144, v135
	v_exp_f32_e32 v135, v132
	v_lshlrev_b32_e32 v146, 6, v136
	v_cvt_pk_bf16_f32 v132, v133, v140
	v_cvt_pk_bf16_f32 v133, v143, v141
	v_add_f32_e32 v212, v135, v134
	v_cvt_pk_bf16_f32 v134, v139, v138
	v_cvt_pk_bf16_f32 v135, v144, v135
	v_add_u32_e32 v144, s63, v137
	v_xad_u32 v145, v137, 16, s63
	v_or_b32_e32 v138, v146, v162
	v_add_u32_e32 v136, v144, v138
	v_add_u32_e32 v138, v145, v138
	ds_read_b64_tr_b16 v[136:137], v136
	ds_read_b64_tr_b16 v[138:139], v138 offset:1024
	v_pk_mul_f32 v[140:141], v[28:29], v[0:1] op_sel_hi:[1,0]
	v_pk_mul_f32 v[142:143], v[30:31], v[0:1] op_sel_hi:[1,0]
	v_cndmask_b32_e32 v29, v141, v29, vcc
	v_cndmask_b32_e32 v31, v143, v31, vcc
	v_cndmask_b32_e32 v30, v142, v30, vcc
	v_cndmask_b32_e32 v28, v140, v28, vcc
	v_pk_mul_f32 v[140:141], v[32:33], v[0:1] op_sel_hi:[1,0]
	v_pk_mul_f32 v[142:143], v[34:35], v[0:1] op_sel_hi:[1,0]
	s_waitcnt lgkmcnt(0)
; #define LAS __attribute__((address_space(3)))
; __device__ __forceinline__ s16x4 vtr(const LAS unsigned char* p) { return __builtin_bit_cast(s16x4, __builtin_amdgcn_ds_read_tr16_b64_v4i16((LAS s16x4*)p)); }
; __device__ __forceinline__ bf16x8 cat4(s16x4 a, s16x4 b) { return __builtin_shufflevector(a, b, 0, 1, 2, 3, 4, 5, 6, 7); }
; template <class Bias>
; __device__ __forceinline__ void attn_softmax_pv(const f32x4& sa, const f32x4& sb, float ra, float rb, const LAS unsigned char* vt, int lane, float& m, float& l, f32x4 (&O)[8], Bias bias) {
;     ...
;     for (int db = 0; db < 8; ++db) {
;         const s16x4 v0 = vtr(vt + tra.b0 + 32u * ((unsigned)db ^ tra.x0)), v1 = vtr(vt + tra.b1 + 32u * ((unsigned)db ^ tra.x1));
;         if (resc) O[db] = O[db] * corr;
;         O[db] = __builtin_amdgcn_mfma_f32_16x16x32_bf16(cat4(v0, v1), pf, O[db], 0, 0, 0);
;     }
; __device__ __forceinline__ void v_to_lds(LAS unsigned char* vt, const bf16x8 (&vn)[8], int lane) {
; #pragma unroll
;     for (int it = 0; it < 8; ++it) *(LAS bf16x8*)(vt + off_b(it * 4 + (lane >> 4), lane & 15)) = vn[it];
; }
	v_mfma_f32_16x16x32_bf16 v[28:31], v[136:139], v[132:135], v[28:31]
	v_bitop3_b32 v138, v146, 32, v147 bitop3:0x34
	v_add_u32_e32 v136, v144, v138
	v_add_u32_e32 v138, v145, v138
	ds_read_b64_tr_b16 v[136:137], v136
	ds_read_b64_tr_b16 v[138:139], v138 offset:1024
	v_cndmask_b32_e32 v35, v143, v35, vcc
	v_cndmask_b32_e32 v34, v142, v34, vcc
	v_cndmask_b32_e32 v33, v141, v33, vcc
	v_cndmask_b32_e32 v32, v140, v32, vcc
	v_pk_mul_f32 v[140:141], v[20:21], v[0:1] op_sel_hi:[1,0]
	v_pk_mul_f32 v[142:143], v[22:23], v[0:1] op_sel_hi:[1,0]
	s_waitcnt lgkmcnt(0)
	v_mfma_f32_16x16x32_bf16 v[32:35], v[136:139], v[132:135], v[32:35]
	v_bitop3_b32 v138, v146, 64, v162 bitop3:0x36
	v_add_u32_e32 v136, v144, v138
	v_add_u32_e32 v138, v145, v138
	ds_read_b64_tr_b16 v[136:137], v136
	ds_read_b64_tr_b16 v[138:139], v138 offset:1024
	v_cndmask_b32_e32 v23, v143, v23, vcc
	v_cndmask_b32_e32 v22, v142, v22, vcc
	v_cndmask_b32_e32 v21, v141, v21, vcc
	v_cndmask_b32_e32 v20, v140, v20, vcc
	v_pk_mul_f32 v[140:141], v[24:25], v[0:1] op_sel_hi:[1,0]
	v_pk_mul_f32 v[142:143], v[26:27], v[0:1] op_sel_hi:[1,0]
	s_waitcnt lgkmcnt(0)
	v_mfma_f32_16x16x32_bf16 v[20:23], v[136:139], v[132:135], v[20:23]
	v_bitop3_b32 v138, v146, s14, v162 bitop3:0x36
	v_add_u32_e32 v136, v144, v138
	v_add_u32_e32 v138, v145, v138
	ds_read_b64_tr_b16 v[136:137], v136
	ds_read_b64_tr_b16 v[138:139], v138 offset:1024
	v_cndmask_b32_e32 v27, v143, v27, vcc
	v_cndmask_b32_e32 v26, v142, v26, vcc
	v_cndmask_b32_e32 v25, v141, v25, vcc
	v_cndmask_b32_e32 v24, v140, v24, vcc
	v_pk_mul_f32 v[140:141], v[12:13], v[0:1] op_sel_hi:[1,0]
	v_pk_mul_f32 v[142:143], v[14:15], v[0:1] op_sel_hi:[1,0]
	s_waitcnt lgkmcnt(0)
	v_mfma_f32_16x16x32_bf16 v[24:27], v[136:139], v[132:135], v[24:27]
	v_bitop3_b32 v138, v146, s16, v162 bitop3:0x36
	v_add_u32_e32 v136, v144, v138
	v_add_u32_e32 v138, v145, v138
	ds_read_b64_tr_b16 v[136:137], v136
	ds_read_b64_tr_b16 v[138:139], v138 offset:1024
	v_cndmask_b32_e32 v15, v143, v15, vcc
	v_cndmask_b32_e32 v14, v142, v14, vcc
	v_cndmask_b32_e32 v13, v141, v13, vcc
	v_cndmask_b32_e32 v12, v140, v12, vcc
	v_pk_mul_f32 v[140:141], v[16:17], v[0:1] op_sel_hi:[1,0]
	v_pk_mul_f32 v[142:143], v[18:19], v[0:1] op_sel_hi:[1,0]
	s_waitcnt lgkmcnt(0)
	v_mfma_f32_16x16x32_bf16 v[12:15], v[136:139], v[132:135], v[12:15]
	v_bitop3_b32 v138, v146, s17, v162 bitop3:0x36
	v_add_u32_e32 v136, v144, v138
	v_add_u32_e32 v138, v145, v138
	ds_read_b64_tr_b16 v[136:137], v136
	ds_read_b64_tr_b16 v[138:139], v138 offset:1024
	v_cndmask_b32_e32 v19, v143, v19, vcc
	v_cndmask_b32_e32 v18, v142, v18, vcc
	v_cndmask_b32_e32 v17, v141, v17, vcc
	v_cndmask_b32_e32 v16, v140, v16, vcc
	v_pk_mul_f32 v[140:141], v[4:5], v[0:1] op_sel_hi:[1,0]
	v_pk_mul_f32 v[142:143], v[6:7], v[0:1] op_sel_hi:[1,0]
	s_waitcnt lgkmcnt(0)
	v_mfma_f32_16x16x32_bf16 v[16:19], v[136:139], v[132:135], v[16:19]
	v_bitop3_b32 v138, v146, s12, v162 bitop3:0x36
	v_add_u32_e32 v136, v144, v138
	v_add_u32_e32 v138, v145, v138
	ds_read_b64_tr_b16 v[136:137], v136
	ds_read_b64_tr_b16 v[138:139], v138 offset:1024
	v_cndmask_b32_e32 v7, v143, v7, vcc
	v_cndmask_b32_e32 v6, v142, v6, vcc
	v_cndmask_b32_e32 v5, v141, v5, vcc
	v_cndmask_b32_e32 v4, v140, v4, vcc
	v_pk_mul_f32 v[140:141], v[8:9], v[0:1] op_sel_hi:[1,0]
	v_pk_mul_f32 v[142:143], v[10:11], v[0:1] op_sel_hi:[1,0]
	s_waitcnt lgkmcnt(0)
	v_mfma_f32_16x16x32_bf16 v[4:7], v[136:139], v[132:135], v[4:7]
	v_bitop3_b32 v138, v146, s93, v162 bitop3:0x36
	v_add_u32_e32 v136, v144, v138
	v_add_u32_e32 v138, v145, v138
	ds_read_b64_tr_b16 v[136:137], v136
	ds_read_b64_tr_b16 v[138:139], v138 offset:1024
	v_cndmask_b32_e32 v11, v143, v11, vcc
	v_cndmask_b32_e32 v10, v142, v10, vcc
	v_cndmask_b32_e32 v9, v141, v9, vcc
	v_cndmask_b32_e32 v8, v140, v8, vcc
	v_fmac_f32_e32 v212, v211, v0
	s_andn2_b64 vcc, exec, s[6:7]
	s_waitcnt lgkmcnt(0)
	v_mfma_f32_16x16x32_bf16 v[8:11], v[136:139], v[132:135], v[8:11]
	s_cbranch_vccnz .LBB0_1562
	s_andn2_b64 vcc, exec, s[8:9]
	s_cbranch_vccnz .Ldil_lad7b
	s_waitcnt vmcnt(15)
	ds_write_b128 v203, v[72:75]
	s_waitcnt vmcnt(14)
	ds_write_b128 v204, v[68:71]
	s_waitcnt vmcnt(13)
	ds_write_b128 v205, v[80:83]
	s_waitcnt vmcnt(12)
	ds_write_b128 v206, v[76:79]
	s_waitcnt vmcnt(11)
	ds_write_b128 v207, v[88:91]
	s_waitcnt vmcnt(10)
	ds_write_b128 v208, v[84:87]
	s_waitcnt vmcnt(9)
	ds_write_b128 v209, v[92:95]
	s_waitcnt vmcnt(8)
	ds_write_b128 v210, v[128:131]
	s_branch .Ldil_ladjb

; __device__ __forceinline__ bool dil_inrange(int pos0, int d, int u0) { return (pos0 + d * u0 >= 0) && (pos0 + d * (u0 + 31) < SEQ); }
; __device__ __forceinline__ void dil_loadv(bf16x8 (&vn)[8], const bf16* Vb, int pos0, int d, int u0, int fq) {
;     if (dil_inrange(pos0, d, u0)) {
;         const bf16* p = Vb + (size_t)(pos0 + d * (u0 + fq)) * 128; const size_t step = (size_t)(512 * d);
; #pragma unroll
;         for (int it = 0; it < 8; ++it) vn[it] = *(const bf16x8*)(p + (size_t)it * step);
;     } else {
; #pragma unroll
;         for (int it = 0; it < 8; ++it) { int pos = pos0 + d * (u0 + it * 4 + fq); pos = pos < 0 ? 0 : (pos > SEQ - 1 ? SEQ - 1 : pos); vn[it] = *(const bf16x8*)(Vb + (size_t)pos * 128); }
;     }
.Ldil_ladjb:
	s_cbranch_vccnz .LBB0_1599
	v_add_u32_e32 v129, s5, v166
	s_sub_i32 s6, s5, 32
	v_subrev_u32_e32 v0, 63, v129
	s_lshl_b32 s6, s6, s23
	v_lshlrev_b32_e32 v0, s23, v0
	s_cmp_lt_u32 s6, s22
	v_add_u32_e32 v128, s65, v0
	s_mov_b64 s[6:7], -1
	s_cbranch_scc1 .LBB0_1596
	v_med3_i32 v0, v128, 0, v225
	v_lshlrev_b32_e32 v0, 8, v0
	v_lshl_add_u64 v[68:69], v[160:161], 0, v[0:1]
	v_subrev_u32_e32 v0, 59, v129
	v_lshlrev_b32_e32 v0, s23, v0
	v_add_u32_e32 v0, s65, v0
	v_med3_i32 v0, v0, 0, v225
	v_lshlrev_b32_e32 v0, 8, v0
	v_lshl_add_u64 v[70:71], v[160:161], 0, v[0:1]
	v_subrev_u32_e32 v0, 55, v129
	v_lshlrev_b32_e32 v0, s23, v0
	v_add_u32_e32 v0, s65, v0
	v_med3_i32 v0, v0, 0, v225
	v_lshlrev_b32_e32 v0, 8, v0
	v_lshl_add_u64 v[76:77], v[160:161], 0, v[0:1]
	v_subrev_u32_e32 v0, 51, v129
	v_lshlrev_b32_e32 v0, s23, v0
	v_add_u32_e32 v0, s65, v0
	v_med3_i32 v0, v0, 0, v225
	v_lshlrev_b32_e32 v0, 8, v0
	v_lshl_add_u64 v[78:79], v[160:161], 0, v[0:1]
	v_subrev_u32_e32 v0, 47, v129
	v_lshlrev_b32_e32 v0, s23, v0
	v_add_u32_e32 v0, s65, v0
	v_med3_i32 v0, v0, 0, v225
	v_lshlrev_b32_e32 v0, 8, v0
	v_lshl_add_u64 v[84:85], v[160:161], 0, v[0:1]
	v_subrev_u32_e32 v0, 43, v129
	v_lshlrev_b32_e32 v0, s23, v0
	v_add_u32_e32 v0, s65, v0
	v_med3_i32 v0, v0, 0, v225
	v_lshlrev_b32_e32 v0, 8, v0
	v_lshl_add_u64 v[86:87], v[160:161], 0, v[0:1]
	v_subrev_u32_e32 v0, 39, v129
	v_lshlrev_b32_e32 v0, s23, v0
	v_add_u32_e32 v0, s65, v0
	v_med3_i32 v0, v0, 0, v225
	v_lshlrev_b32_e32 v0, 8, v0
	v_lshl_add_u64 v[92:93], v[160:161], 0, v[0:1]
	global_load_dwordx4 v[72:75], v[68:69], off
	s_nop 0
	global_load_dwordx4 v[68:71], v[70:71], off
	s_nop 0
	global_load_dwordx4 v[80:83], v[76:77], off
	s_nop 0
	global_load_dwordx4 v[76:79], v[78:79], off
	s_nop 0
	global_load_dwordx4 v[88:91], v[84:85], off
	s_nop 0
	global_load_dwordx4 v[84:87], v[86:87], off
	v_subrev_u32_e32 v0, 35, v129
	global_load_dwordx4 v[92:95], v[92:93], off
	v_lshlrev_b32_e32 v0, s23, v0
	v_add_u32_e32 v0, s65, v0
	v_med3_i32 v0, v0, 0, v225
	v_lshlrev_b32_e32 v0, 8, v0
	v_lshl_add_u64 v[130:131], v[160:161], 0, v[0:1]
	s_mov_b64 s[6:7], 0
